# panel barriers: three staggered sc1 polls in flight (pipelined polling)
# baseline (speedup 1.0000x reference)
; __device__ __forceinline__ unsigned xb_ld(unsigned* p)              { return __hip_atomic_load(p, __ATOMIC_RELAXED, __HIP_MEMORY_SCOPE_AGENT); }
; __device__ __forceinline__ unsigned xb_add(unsigned* p, unsigned v) { return __hip_atomic_fetch_add(p, v, __ATOMIC_RELAXED, __HIP_MEMORY_SCOPE_AGENT); }
; #define XB_SPIN(cond, bar) do { unsigned _sp = 0; while (cond) { __builtin_amdgcn_s_sleep(1); \
;     if ((++_sp & 255u) == 0u) { if (xb_ld(&(bar)[XB_TMO])) break; if (_sp > XB_SPIN_CAP) { atomicAdd(&(bar)[XB_TMO], 1u); break; } } } } while (0)
; __device__ __forceinline__ void xcd_barrier(const XcdBarrier& b) {
;     asm volatile("s_waitcnt vmcnt(0)" ::: "memory");
;     __syncthreads();
;     if (threadIdx.x == 0) {
;         unsigned* bar = b.bar;
;         __builtin_amdgcn_s_waitcnt(0);
;         unsigned nloc = b.st[0], nx = b.st[1];
;         if (nloc == 0u) { xcd_barrier_complete(bar, b.x, nloc, nx); b.st[0] = nloc; b.st[1] = nx; }
;         const unsigned old = xb_add(&bar[XB_XSUB(b.x)], 1u);
;         const unsigned gen = old / nloc;
;         if (old + 1u == (gen + 1u) * nloc) {
;             __builtin_amdgcn_fence(__ATOMIC_RELEASE, "agent");
;             asm volatile("s_waitcnt vmcnt(0)" ::: "memory");
;             const unsigned og = xb_add(&bar[XB_TOP], 1u);
;             const unsigned tg = og / nx;
;             if (og + 1u == (tg + 1u) * nx) xb_add(&bar[XB_TOPGEN], 1u);
;             else XB_SPIN(xb_ld(&bar[XB_TOPGEN]) == tg, bar);
;             __builtin_amdgcn_fence(__ATOMIC_ACQUIRE, "agent");
;             xb_add(&bar[XB_XGEN(b.x)], 1u);
;             asm volatile("s_waitcnt vmcnt(0)" ::: "memory");
;         } else {
;             XB_SPIN(xb_ld(&bar[XB_XGEN(b.x)]) == gen, bar);
;             __builtin_amdgcn_fence(__ATOMIC_ACQUIRE, "agent");
;             asm volatile("s_waitcnt vmcnt(0)" ::: "memory");
;         }
;     }
;     __syncthreads();
; }
.LBB0_252:
	s_cmp_gt_i32 s85, 2
	s_cselect_b64 s[2:3], -1, 0
	s_and_b64 s[4:5], s[6:7], s[2:3]
	s_andn2_b64 vcc, exec, s[4:5]
	s_cbranch_vccnz .LBB0_306
	s_waitcnt vmcnt(0)
	s_barrier
	s_mov_b64 s[4:5], exec
	v_readlane_b32 s6, v251, 18
	v_readlane_b32 s7, v251, 19
	s_and_b64 s[6:7], s[4:5], s[6:7]
	s_mov_b64 exec, s[6:7]
	s_cbranch_execz .LBB0_305
	buffer_inv sc1
	s_and_b32 s10, s88, 7
	s_lshl_b32 s10, s10, 3
	s_bfe_u32 s11, s88, 0x30003
	s_or_b32 s10, s10, s11
	s_lshl_b32 s10, s10, 8
	s_add_u32 s12, s66, 0xfd09000
	s_addc_u32 s13, s67, 0
	v_mov_b32_e32 v1, s10
	v_mov_b32_e32 v2, 1
	global_atomic_add v1, v2, s[12:13]
	s_movk_i32 s11, 4
	s_mov_b32 s14, 0
	v_mov_b32_e32 v5, 0x6000
	global_load_dword v3, v1, s[12:13] sc1
	global_load_dword v6, v5, s[12:13] sc1
	s_sleep 10
	global_load_dword v4, v1, s[12:13] sc1
	global_load_dword v16, v5, s[12:13] sc1
	s_sleep 10
	global_load_dword v17, v1, s[12:13] sc1
	global_load_dword v18, v5, s[12:13] sc1
	s_sleep 10
.Lls1_spin:
	s_waitcnt vmcnt(4)
	v_readfirstlane_b32 s15, v3
	v_readfirstlane_b32 s10, v6
	s_nop 3
	s_cmp_ge_u32 s15, s11
	s_cselect_b32 s15, 1, 0
	s_cmp_ge_u32 s10, 0x80
	s_cselect_b32 s10, 1, 0
	s_and_b32 s15, s15, s10
	s_cmp_lg_u32 s15, 0
	s_cbranch_scc1 .Lls1_ok
	global_load_dword v3, v1, s[12:13] sc1
	global_load_dword v6, v5, s[12:13] sc1
	s_sleep 10
	s_waitcnt vmcnt(4)
	v_readfirstlane_b32 s15, v4
	v_readfirstlane_b32 s10, v16
	s_nop 3
	s_cmp_ge_u32 s15, s11
	s_cselect_b32 s15, 1, 0
	s_cmp_ge_u32 s10, 0x80
	s_cselect_b32 s10, 1, 0
	s_and_b32 s15, s15, s10
	s_cmp_lg_u32 s15, 0
	s_cbranch_scc1 .Lls1_ok
	global_load_dword v4, v1, s[12:13] sc1
	global_load_dword v16, v5, s[12:13] sc1
	s_sleep 10
	s_waitcnt vmcnt(4)
	v_readfirstlane_b32 s15, v17
	v_readfirstlane_b32 s10, v18
	s_nop 3
	s_cmp_ge_u32 s15, s11
	s_cselect_b32 s15, 1, 0
	s_cmp_ge_u32 s10, 0x80
	s_cselect_b32 s10, 1, 0
	s_and_b32 s15, s15, s10
	s_cmp_lg_u32 s15, 0
	s_cbranch_scc1 .Lls1_ok
	global_load_dword v17, v1, s[12:13] sc1
	global_load_dword v18, v5, s[12:13] sc1
	s_sleep 10
	s_add_i32 s14, s14, 1
	s_cmp_lt_u32 s14, 0x20000
	s_cbranch_scc1 .Lls1_spin

; __device__ __forceinline__ unsigned xb_ld(unsigned* p)              { return __hip_atomic_load(p, __ATOMIC_RELAXED, __HIP_MEMORY_SCOPE_AGENT); }
; __device__ __forceinline__ unsigned xb_add(unsigned* p, unsigned v) { return __hip_atomic_fetch_add(p, v, __ATOMIC_RELAXED, __HIP_MEMORY_SCOPE_AGENT); }
; #define XB_SPIN(cond, bar) do { unsigned _sp = 0; while (cond) { __builtin_amdgcn_s_sleep(1); \
;     if ((++_sp & 255u) == 0u) { if (xb_ld(&(bar)[XB_TMO])) break; if (_sp > XB_SPIN_CAP) { atomicAdd(&(bar)[XB_TMO], 1u); break; } } } } while (0)
; __device__ __forceinline__ void xcd_barrier(const XcdBarrier& b) {
;     asm volatile("s_waitcnt vmcnt(0)" ::: "memory");
;     __syncthreads();
;     if (threadIdx.x == 0) {
;         unsigned* bar = b.bar;
;         __builtin_amdgcn_s_waitcnt(0);
;         unsigned nloc = b.st[0], nx = b.st[1];
;         if (nloc == 0u) { xcd_barrier_complete(bar, b.x, nloc, nx); b.st[0] = nloc; b.st[1] = nx; }
;         const unsigned old = xb_add(&bar[XB_XSUB(b.x)], 1u);
;         const unsigned gen = old / nloc;
;         if (old + 1u == (gen + 1u) * nloc) {
;             __builtin_amdgcn_fence(__ATOMIC_RELEASE, "agent");
;             asm volatile("s_waitcnt vmcnt(0)" ::: "memory");
;             const unsigned og = xb_add(&bar[XB_TOP], 1u);
;             const unsigned tg = og / nx;
;             if (og + 1u == (tg + 1u) * nx) xb_add(&bar[XB_TOPGEN], 1u);
;             else XB_SPIN(xb_ld(&bar[XB_TOPGEN]) == tg, bar);
;             __builtin_amdgcn_fence(__ATOMIC_ACQUIRE, "agent");
;             xb_add(&bar[XB_XGEN(b.x)], 1u);
;             asm volatile("s_waitcnt vmcnt(0)" ::: "memory");
;         } else {
;             XB_SPIN(xb_ld(&bar[XB_XGEN(b.x)]) == gen, bar);
;             __builtin_amdgcn_fence(__ATOMIC_ACQUIRE, "agent");
;             asm volatile("s_waitcnt vmcnt(0)" ::: "memory");
;         }
;     }
;     __syncthreads();
; }
.LBB0_353:
	s_cmp_gt_i32 s85, 3
	s_cselect_b64 s[2:3], -1, 0
	s_and_b64 s[4:5], s[10:11], s[2:3]
	s_andn2_b64 vcc, exec, s[4:5]
	s_cbranch_vccnz .LBB0_407
	s_waitcnt vmcnt(0)
	s_waitcnt lgkmcnt(0)
	s_barrier
	s_mov_b64 s[4:5], exec
	v_readlane_b32 s6, v251, 18
	v_readlane_b32 s7, v251, 19
	s_and_b64 s[6:7], s[4:5], s[6:7]
	s_mov_b64 exec, s[6:7]
	s_cbranch_execz .LBB0_406
	buffer_inv sc1
	s_and_b32 s10, s88, 7
	s_lshl_b32 s10, s10, 3
	s_bfe_u32 s11, s88, 0x30003
	s_or_b32 s10, s10, s11
	s_lshl_b32 s10, s10, 8
	s_add_u32 s12, s66, 0xfd09000
	s_addc_u32 s13, s67, 0
	v_mov_b32_e32 v1, s10
	v_mov_b32_e32 v2, 1
	global_atomic_add v1, v2, s[12:13]
	v_mov_b32_e32 v5, 0x5800
	global_atomic_add v5, v2, s[12:13]
	s_movk_i32 s11, 8
	s_mov_b32 s14, 0
	global_load_dword v3, v1, s[12:13] sc1
	s_sleep 10
	global_load_dword v4, v1, s[12:13] sc1
	s_sleep 10
	global_load_dword v17, v1, s[12:13] sc1
	s_sleep 10
.Lls2_spin:
	s_waitcnt vmcnt(2)
	v_readfirstlane_b32 s15, v3
	s_nop 3
	s_cmp_ge_u32 s15, s11
	s_cbranch_scc1 .Lls2_ok
	global_load_dword v3, v1, s[12:13] sc1
	s_sleep 10
	s_waitcnt vmcnt(2)
	v_readfirstlane_b32 s15, v4
	s_nop 3
	s_cmp_ge_u32 s15, s11
	s_cbranch_scc1 .Lls2_ok
	global_load_dword v4, v1, s[12:13] sc1
	s_sleep 10
	s_waitcnt vmcnt(2)
	v_readfirstlane_b32 s15, v17
	s_nop 3
	s_cmp_ge_u32 s15, s11
	s_cbranch_scc1 .Lls2_ok
	global_load_dword v17, v1, s[12:13] sc1
	s_sleep 10
	s_add_i32 s14, s14, 1
	s_cmp_lt_u32 s14, 0x20000
	s_cbranch_scc1 .Lls2_spin

; __device__ __forceinline__ unsigned xb_ld(unsigned* p)              { return __hip_atomic_load(p, __ATOMIC_RELAXED, __HIP_MEMORY_SCOPE_AGENT); }
; __device__ __forceinline__ unsigned xb_add(unsigned* p, unsigned v) { return __hip_atomic_fetch_add(p, v, __ATOMIC_RELAXED, __HIP_MEMORY_SCOPE_AGENT); }
; #define XB_SPIN(cond, bar) do { unsigned _sp = 0; while (cond) { __builtin_amdgcn_s_sleep(1); \
;     if ((++_sp & 255u) == 0u) { if (xb_ld(&(bar)[XB_TMO])) break; if (_sp > XB_SPIN_CAP) { atomicAdd(&(bar)[XB_TMO], 1u); break; } } } } while (0)
; __device__ __forceinline__ void xcd_barrier(const XcdBarrier& b) {
;     asm volatile("s_waitcnt vmcnt(0)" ::: "memory");
;     __syncthreads();
;     if (threadIdx.x == 0) {
;         unsigned* bar = b.bar;
;         __builtin_amdgcn_s_waitcnt(0);
;         unsigned nloc = b.st[0], nx = b.st[1];
;         if (nloc == 0u) { xcd_barrier_complete(bar, b.x, nloc, nx); b.st[0] = nloc; b.st[1] = nx; }
;         const unsigned old = xb_add(&bar[XB_XSUB(b.x)], 1u);
;         const unsigned gen = old / nloc;
;         if (old + 1u == (gen + 1u) * nloc) {
;             __builtin_amdgcn_fence(__ATOMIC_RELEASE, "agent");
;             asm volatile("s_waitcnt vmcnt(0)" ::: "memory");
;             const unsigned og = xb_add(&bar[XB_TOP], 1u);
;             const unsigned tg = og / nx;
;             if (og + 1u == (tg + 1u) * nx) xb_add(&bar[XB_TOPGEN], 1u);
;             else XB_SPIN(xb_ld(&bar[XB_TOPGEN]) == tg, bar);
;             __builtin_amdgcn_fence(__ATOMIC_ACQUIRE, "agent");
;             xb_add(&bar[XB_XGEN(b.x)], 1u);
;             asm volatile("s_waitcnt vmcnt(0)" ::: "memory");
;         } else {
;             XB_SPIN(xb_ld(&bar[XB_XGEN(b.x)]) == gen, bar);
;             __builtin_amdgcn_fence(__ATOMIC_ACQUIRE, "agent");
;             asm volatile("s_waitcnt vmcnt(0)" ::: "memory");
;         }
;     }
;     __syncthreads();
; }
.LBB0_1138:
	s_cmp_gt_i32 s85, 9
	s_cselect_b64 s[0:1], -1, 0
	s_and_b64 s[2:3], s[4:5], s[0:1]
	s_andn2_b64 vcc, exec, s[2:3]
	s_cbranch_vccnz .LBB0_1192
	s_waitcnt vmcnt(0)
	s_waitcnt vmcnt(0) lgkmcnt(0)
	s_barrier
	s_and_saveexec_b64 s[2:3], s[74:75]
	s_cbranch_execz .LBB0_1191
	buffer_inv sc1
	s_and_b32 s4, s88, 7
	s_lshl_b32 s4, s4, 3
	s_bfe_u32 s5, s88, 0x30003
	s_or_b32 s4, s4, s5
	s_lshl_b32 s4, s4, 8
	s_add_u32 s6, s66, 0xfd09000
	s_addc_u32 s7, s67, 0
	v_mov_b32_e32 v1, s4
	v_mov_b32_e32 v2, 1
	global_atomic_add v1, v2, s[6:7]
	v_mov_b32_e32 v5, 0x5000
	global_atomic_add v5, v2, s[6:7]
	s_movk_i32 s5, 12
	s_mov_b32 s8, 0
	global_load_dword v3, v1, s[6:7] sc1
	s_sleep 10
	global_load_dword v4, v1, s[6:7] sc1
	s_sleep 10
	global_load_dword v17, v1, s[6:7] sc1
	s_sleep 10
.Lls8_spin:
	s_waitcnt vmcnt(2)
	v_readfirstlane_b32 s9, v3
	s_nop 3
	s_cmp_ge_u32 s9, s5
	s_cbranch_scc1 .Lls8_ok
	global_load_dword v3, v1, s[6:7] sc1
	s_sleep 10
	s_waitcnt vmcnt(2)
	v_readfirstlane_b32 s9, v4
	s_nop 3
	s_cmp_ge_u32 s9, s5
	s_cbranch_scc1 .Lls8_ok
	global_load_dword v4, v1, s[6:7] sc1
	s_sleep 10
	s_waitcnt vmcnt(2)
	v_readfirstlane_b32 s9, v17
	s_nop 3
	s_cmp_ge_u32 s9, s5
	s_cbranch_scc1 .Lls8_ok
	global_load_dword v17, v1, s[6:7] sc1
	s_sleep 10
	s_add_i32 s8, s8, 1
	s_cmp_lt_u32 s8, 0x20000
	s_cbranch_scc1 .Lls8_spin

; __device__ __forceinline__ unsigned xb_ld(unsigned* p)              { return __hip_atomic_load(p, __ATOMIC_RELAXED, __HIP_MEMORY_SCOPE_AGENT); }
; __device__ __forceinline__ unsigned xb_add(unsigned* p, unsigned v) { return __hip_atomic_fetch_add(p, v, __ATOMIC_RELAXED, __HIP_MEMORY_SCOPE_AGENT); }
; #define XB_SPIN(cond, bar) do { unsigned _sp = 0; while (cond) { __builtin_amdgcn_s_sleep(1); \
;     if ((++_sp & 255u) == 0u) { if (xb_ld(&(bar)[XB_TMO])) break; if (_sp > XB_SPIN_CAP) { atomicAdd(&(bar)[XB_TMO], 1u); break; } } } } while (0)
; __device__ __forceinline__ void xcd_barrier(const XcdBarrier& b) {
;     asm volatile("s_waitcnt vmcnt(0)" ::: "memory");
;     __syncthreads();
;     if (threadIdx.x == 0) {
;         unsigned* bar = b.bar;
;         __builtin_amdgcn_s_waitcnt(0);
;         unsigned nloc = b.st[0], nx = b.st[1];
;         if (nloc == 0u) { xcd_barrier_complete(bar, b.x, nloc, nx); b.st[0] = nloc; b.st[1] = nx; }
;         const unsigned old = xb_add(&bar[XB_XSUB(b.x)], 1u);
;         const unsigned gen = old / nloc;
;         if (old + 1u == (gen + 1u) * nloc) {
;             __builtin_amdgcn_fence(__ATOMIC_RELEASE, "agent");
;             asm volatile("s_waitcnt vmcnt(0)" ::: "memory");
;             const unsigned og = xb_add(&bar[XB_TOP], 1u);
;             const unsigned tg = og / nx;
;             if (og + 1u == (tg + 1u) * nx) xb_add(&bar[XB_TOPGEN], 1u);
;             else XB_SPIN(xb_ld(&bar[XB_TOPGEN]) == tg, bar);
;             __builtin_amdgcn_fence(__ATOMIC_ACQUIRE, "agent");
;             xb_add(&bar[XB_XGEN(b.x)], 1u);
;             asm volatile("s_waitcnt vmcnt(0)" ::: "memory");
;         } else {
;             XB_SPIN(xb_ld(&bar[XB_XGEN(b.x)]) == gen, bar);
;             __builtin_amdgcn_fence(__ATOMIC_ACQUIRE, "agent");
;             asm volatile("s_waitcnt vmcnt(0)" ::: "memory");
;         }
;     }
;     __syncthreads();
; }
.LBB0_1235:
	s_cmp_gt_i32 s85, 10
	s_cselect_b64 s[2:3], -1, 0
	s_and_b64 s[0:1], s[0:1], s[2:3]
	s_andn2_b64 vcc, exec, s[0:1]
	s_cbranch_vccnz .LBB0_1289
	s_waitcnt vmcnt(0)
	s_waitcnt vmcnt(0) lgkmcnt(0)
	s_barrier
	s_and_saveexec_b64 s[0:1], s[74:75]
	s_cbranch_execz .LBB0_1288
	buffer_inv sc1
	s_and_b32 s4, s88, 7
	s_lshl_b32 s4, s4, 3
	s_bfe_u32 s5, s88, 0x30003
	s_or_b32 s4, s4, s5
	s_lshl_b32 s4, s4, 8
	s_add_u32 s6, s66, 0xfd09000
	s_addc_u32 s7, s67, 0
	v_mov_b32_e32 v1, s4
	v_mov_b32_e32 v2, 1
	global_atomic_add v1, v2, s[6:7]
	s_movk_i32 s5, 16
	s_mov_b32 s8, 0
	v_mov_b32_e32 v5, 0x5000
	global_load_dword v3, v1, s[6:7] sc1
	global_load_dword v6, v5, s[6:7] sc1
	s_sleep 10
	global_load_dword v4, v1, s[6:7] sc1
	global_load_dword v16, v5, s[6:7] sc1
	s_sleep 10
	global_load_dword v17, v1, s[6:7] sc1
	global_load_dword v18, v5, s[6:7] sc1
	s_sleep 10
.Lls9_spin:
	s_waitcnt vmcnt(4)
	v_readfirstlane_b32 s9, v3
	v_readfirstlane_b32 s4, v6
	s_nop 3
	s_cmp_ge_u32 s9, s5
	s_cselect_b32 s9, 1, 0
	s_cmp_ge_u32 s4, s86
	s_cselect_b32 s4, 1, 0
	s_and_b32 s9, s9, s4
	s_cmp_lg_u32 s9, 0
	s_cbranch_scc1 .Lls9_ok
	global_load_dword v3, v1, s[6:7] sc1
	global_load_dword v6, v5, s[6:7] sc1
	s_sleep 10
	s_waitcnt vmcnt(4)
	v_readfirstlane_b32 s9, v4
	v_readfirstlane_b32 s4, v16
	s_nop 3
	s_cmp_ge_u32 s9, s5
	s_cselect_b32 s9, 1, 0
	s_cmp_ge_u32 s4, s86
	s_cselect_b32 s4, 1, 0
	s_and_b32 s9, s9, s4
	s_cmp_lg_u32 s9, 0
	s_cbranch_scc1 .Lls9_ok
	global_load_dword v4, v1, s[6:7] sc1
	global_load_dword v16, v5, s[6:7] sc1
	s_sleep 10
	s_waitcnt vmcnt(4)
	v_readfirstlane_b32 s9, v17
	v_readfirstlane_b32 s4, v18
	s_nop 3
	s_cmp_ge_u32 s9, s5
	s_cselect_b32 s9, 1, 0
	s_cmp_ge_u32 s4, s86
	s_cselect_b32 s4, 1, 0
	s_and_b32 s9, s9, s4
	s_cmp_lg_u32 s9, 0
	s_cbranch_scc1 .Lls9_ok
	global_load_dword v17, v1, s[6:7] sc1
	global_load_dword v18, v5, s[6:7] sc1
	s_sleep 10
	s_add_i32 s8, s8, 1
	s_cmp_lt_u32 s8, 0x20000
	s_cbranch_scc1 .Lls9_spin

; __device__ __forceinline__ unsigned xb_ld(unsigned* p)              { return __hip_atomic_load(p, __ATOMIC_RELAXED, __HIP_MEMORY_SCOPE_AGENT); }
; __device__ __forceinline__ unsigned xb_add(unsigned* p, unsigned v) { return __hip_atomic_fetch_add(p, v, __ATOMIC_RELAXED, __HIP_MEMORY_SCOPE_AGENT); }
; #define XB_SPIN(cond, bar) do { unsigned _sp = 0; while (cond) { __builtin_amdgcn_s_sleep(1); \
;     if ((++_sp & 255u) == 0u) { if (xb_ld(&(bar)[XB_TMO])) break; if (_sp > XB_SPIN_CAP) { atomicAdd(&(bar)[XB_TMO], 1u); break; } } } } while (0)
; __device__ __forceinline__ void xcd_barrier(const XcdBarrier& b) {
;     asm volatile("s_waitcnt vmcnt(0)" ::: "memory");
;     __syncthreads();
;     if (threadIdx.x == 0) {
;         unsigned* bar = b.bar;
;         __builtin_amdgcn_s_waitcnt(0);
;         unsigned nloc = b.st[0], nx = b.st[1];
;         if (nloc == 0u) { xcd_barrier_complete(bar, b.x, nloc, nx); b.st[0] = nloc; b.st[1] = nx; }
;         const unsigned old = xb_add(&bar[XB_XSUB(b.x)], 1u);
;         const unsigned gen = old / nloc;
;         if (old + 1u == (gen + 1u) * nloc) {
;             __builtin_amdgcn_fence(__ATOMIC_RELEASE, "agent");
;             asm volatile("s_waitcnt vmcnt(0)" ::: "memory");
;             const unsigned og = xb_add(&bar[XB_TOP], 1u);
;             const unsigned tg = og / nx;
;             if (og + 1u == (tg + 1u) * nx) xb_add(&bar[XB_TOPGEN], 1u);
;             else XB_SPIN(xb_ld(&bar[XB_TOPGEN]) == tg, bar);
;             __builtin_amdgcn_fence(__ATOMIC_ACQUIRE, "agent");
;             xb_add(&bar[XB_XGEN(b.x)], 1u);
;             asm volatile("s_waitcnt vmcnt(0)" ::: "memory");
;         } else {
;             XB_SPIN(xb_ld(&bar[XB_XGEN(b.x)]) == gen, bar);
;             __builtin_amdgcn_fence(__ATOMIC_ACQUIRE, "agent");
;             asm volatile("s_waitcnt vmcnt(0)" ::: "memory");
;         }
;     }
;     __syncthreads();
; }
.LBB0_1327:
	s_cmp_gt_i32 s85, 11
	s_cselect_b64 s[2:3], -1, 0
	s_and_b64 s[0:1], s[0:1], s[2:3]
	v_readlane_b32 s48, v252, 22
	s_andn2_b64 vcc, exec, s[0:1]
	v_readlane_b32 s49, v252, 23
	s_cbranch_vccnz .LBB0_1381
	s_waitcnt vmcnt(0)
	s_waitcnt vmcnt(0) lgkmcnt(0)
	s_barrier
	s_and_saveexec_b64 s[0:1], s[74:75]
	s_cbranch_execz .LBB0_1380
	buffer_inv sc1
	s_and_b32 s4, s88, 7
	s_lshl_b32 s4, s4, 3
	s_bfe_u32 s5, s88, 0x30003
	s_or_b32 s4, s4, s5
	s_lshl_b32 s4, s4, 8
	s_add_u32 s6, s66, 0xfd09000
	s_addc_u32 s7, s67, 0
	v_mov_b32_e32 v1, s4
	v_mov_b32_e32 v2, 1
	global_atomic_add v1, v2, s[6:7]
	s_movk_i32 s5, 20
	s_mov_b32 s8, 0
	global_load_dword v3, v1, s[6:7] sc1
	s_sleep 10
	global_load_dword v4, v1, s[6:7] sc1
	s_sleep 10
	global_load_dword v17, v1, s[6:7] sc1
	s_sleep 10

; __device__ __forceinline__ unsigned xb_ld(unsigned* p)              { return __hip_atomic_load(p, __ATOMIC_RELAXED, __HIP_MEMORY_SCOPE_AGENT); }
; __device__ __forceinline__ unsigned xb_add(unsigned* p, unsigned v) { return __hip_atomic_fetch_add(p, v, __ATOMIC_RELAXED, __HIP_MEMORY_SCOPE_AGENT); }
; #define XB_SPIN(cond, bar) do { unsigned _sp = 0; while (cond) { __builtin_amdgcn_s_sleep(1); \
;     if ((++_sp & 255u) == 0u) { if (xb_ld(&(bar)[XB_TMO])) break; if (_sp > XB_SPIN_CAP) { atomicAdd(&(bar)[XB_TMO], 1u); break; } } } } while (0)
; __device__ __forceinline__ void xcd_barrier(const XcdBarrier& b) {
;     asm volatile("s_waitcnt vmcnt(0)" ::: "memory");
;     __syncthreads();
;     if (threadIdx.x == 0) {
;         unsigned* bar = b.bar;
;         __builtin_amdgcn_s_waitcnt(0);
;         unsigned nloc = b.st[0], nx = b.st[1];
;         if (nloc == 0u) { xcd_barrier_complete(bar, b.x, nloc, nx); b.st[0] = nloc; b.st[1] = nx; }
;         const unsigned old = xb_add(&bar[XB_XSUB(b.x)], 1u);
;         const unsigned gen = old / nloc;
;         if (old + 1u == (gen + 1u) * nloc) {
;             __builtin_amdgcn_fence(__ATOMIC_RELEASE, "agent");
;             asm volatile("s_waitcnt vmcnt(0)" ::: "memory");
;             const unsigned og = xb_add(&bar[XB_TOP], 1u);
;             const unsigned tg = og / nx;
;             if (og + 1u == (tg + 1u) * nx) xb_add(&bar[XB_TOPGEN], 1u);
;             else XB_SPIN(xb_ld(&bar[XB_TOPGEN]) == tg, bar);
;             __builtin_amdgcn_fence(__ATOMIC_ACQUIRE, "agent");
;             xb_add(&bar[XB_XGEN(b.x)], 1u);
;             asm volatile("s_waitcnt vmcnt(0)" ::: "memory");
;         } else {
;             XB_SPIN(xb_ld(&bar[XB_XGEN(b.x)]) == gen, bar);
;             __builtin_amdgcn_fence(__ATOMIC_ACQUIRE, "agent");
;             asm volatile("s_waitcnt vmcnt(0)" ::: "memory");
;         }
;     }
;     __syncthreads();
; }
.LBB0_1428:
	s_cmp_gt_i32 s85, 12
	s_cselect_b64 s[2:3], -1, 0
	s_and_b64 s[0:1], s[0:1], s[2:3]
	s_andn2_b64 vcc, exec, s[0:1]
	s_cbranch_vccnz .LBB0_1482
	s_waitcnt vmcnt(0)
	s_waitcnt vmcnt(0) lgkmcnt(0)
	s_barrier
	s_and_saveexec_b64 s[0:1], s[74:75]
	s_cbranch_execz .LBB0_1481
	buffer_inv sc1
	s_and_b32 s4, s88, 7
	s_lshl_b32 s4, s4, 3
	s_bfe_u32 s5, s88, 0x30003
	s_or_b32 s4, s4, s5
	s_lshl_b32 s4, s4, 8
	s_add_u32 s6, s66, 0xfd09000
	s_addc_u32 s7, s67, 0
	v_mov_b32_e32 v1, s4
	v_mov_b32_e32 v2, 1
	global_atomic_add v1, v2, s[6:7]
	s_movk_i32 s5, 24
	s_mov_b32 s8, 0
	global_load_dword v3, v1, s[6:7] sc1
	s_sleep 10
	global_load_dword v4, v1, s[6:7] sc1
	s_sleep 10
	global_load_dword v17, v1, s[6:7] sc1
	s_sleep 10
